# work-queue fetch slot: flat (sc0 sc1) LDS store/load replaced by ds_write_b32/ds_read_b32, dropping the vmcnt(0) waits that also drained the previous unit's store acks
# baseline (speedup 1.0000x reference)
.LBB0_162:
	s_or_b64 exec, exec, s[2:3]
	s_mov_b64 s[2:3], src_shared_base
	s_waitcnt vmcnt(0)
	v_readfirstlane_b32 s2, v1
	s_nop 1
	v_add_u32_e32 v0, s2, v0
	v_readlane_b32 s2, v253, 19
	s_nop 1
	v_lshl_or_b32 v2, v0, 3, s2
	s_add_i32 s2, 0, 0x11fe0
	s_cmp_lg_u32 s2, -1
	s_cselect_b32 s2, s2, 0
	s_cselect_b32 s3, s3, 0
	v_mov_b32_e32 v0, s2
	v_mov_b32_e32 v1, s3
	ds_write_b32 v0, v2
.LBB0_163:
	s_or_b64 exec, exec, s[0:1]
	s_mov_b64 s[0:1], src_shared_base
	s_add_i32 s0, 0, 0x11fe0
	s_cmp_lg_u32 s0, -1
	s_cselect_b32 s0, s0, 0
	s_cselect_b32 s1, s1, 0
	v_mov_b32_e32 v0, s0
	v_mov_b32_e32 v1, s1
	s_waitcnt lgkmcnt(0)
	s_barrier
	ds_read_b32 v8, v0
	s_waitcnt lgkmcnt(0)
	s_movk_i32 s0, 0x880
	s_waitcnt lgkmcnt(0)
	v_cmp_gt_i32_e32 vcc, s0, v8
	s_mov_b64 s[0:1], -1
	s_and_saveexec_b64 s[26:27], vcc
	s_cbranch_execz .LBB0_158
	s_movk_i32 s0, 0x1ff
	v_cmp_lt_i32_e32 vcc, s0, v8
	s_and_saveexec_b64 s[0:1], vcc
	s_xor_b64 s[48:49], exec, s[0:1]
	s_cbranch_execz .LBB0_197
	s_movk_i32 s0, 0x5ff
	v_cmp_lt_u32_e32 vcc, s0, v8
	s_and_saveexec_b64 s[0:1], vcc
	s_xor_b64 s[2:3], exec, s[0:1]
	s_cbranch_execz .LBB0_167
	s_movk_i32 s0, 0x67f
	v_cmp_lt_u32_e32 vcc, s0, v8
	v_mov_b32_e32 v0, 0xfffffa00
	v_mov_b32_e32 v1, 0xfffff980
	v_cndmask_b32_e32 v0, v0, v1, vcc
	v_cndmask_b32_e64 v2, 4, 2, vcc
	v_cndmask_b32_e64 v1, 6, 4, vcc
	v_cndmask_b32_e64 v3, 3, 1, vcc
	v_add_u32_e32 v0, v0, v8
	v_lshrrev_b32_e32 v2, v2, v8
	v_lshrrev_b32_e32 v128, v1, v0
	v_lshrrev_b32_e32 v3, v3, v8
	v_mov_b32_e32 v0, 0x2000
	v_lshlrev_b32_e32 v2, 7, v2
	v_lshl_add_u32 v0, v128, 10, v0
	v_lshlrev_b32_e32 v1, 8, v128
	v_and_b32_e32 v130, 0x180, v2
	v_lshlrev_b32_e32 v2, 7, v3
	v_mov_b32_e32 v104, v166
	v_cndmask_b32_e64 v4, 7, 1, vcc
	v_cndmask_b32_e32 v0, v0, v1, vcc
	s_barrier
	v_mov_b32_e32 v1, v129
	v_readlane_b32 s0, v251, 32
	v_and_b32_e32 v132, 0x80, v2
	v_and_b32_e32 v4, v4, v8
	v_ashrrev_i32_e32 v6, 3, v104
	v_lshlrev_b64 v[0:1], 10, v[0:1]
	v_readlane_b32 s1, v251, 33
	v_add_u32_e32 v2, v6, v132
	v_lshlrev_b32_e32 v133, 7, v4
	v_lshl_add_u64 v[0:1], s[0:1], 0, v[0:1]
	v_ashrrev_i32_e32 v3, 31, v2
	v_readlane_b32 s0, v250, 37
	v_lshlrev_b64 v[34:35], 20, v[128:129]
	v_lshlrev_b64 v[32:33], 18, v[128:129]
	v_lshlrev_b32_e32 v128, 1, v130
	v_lshlrev_b64 v[2:3], 8, v[2:3]
	v_readlane_b32 s1, v250, 38
	v_lshlrev_b32_e32 v7, 4, v104
	v_add_u32_e32 v4, v6, v133
	v_lshl_add_u64 v[0:1], v[0:1], 0, v[128:129]
	v_lshl_add_u64 v[2:3], s[0:1], 0, v[2:3]
	v_and_b32_e32 v128, 0x70, v7
	v_ashrrev_i32_e32 v5, 31, v4
	v_lshl_add_u64 v[2:3], v[2:3], 0, v[128:129]
	v_lshlrev_b64 v[4:5], 10, v[4:5]
	s_movk_i32 s0, 0x2000
	v_lshl_add_u64 v[0:1], v[0:1], 0, v[4:5]
	v_add_co_u32_e64 v4, s[0:1], s0, v2
	global_load_dwordx4 v[12:15], v[2:3], off
	s_nop 0
	v_addc_co_u32_e64 v5, s[0:1], 0, v3, s[0:1]
	s_movk_i32 s0, 0x4000
	s_nop 0
	v_add_co_u32_e64 v8, s[0:1], s0, v2
	global_load_dwordx4 v[16:19], v[4:5], off
	s_nop 0
	v_addc_co_u32_e64 v9, s[0:1], 0, v3, s[0:1]
	global_load_dwordx4 v[20:23], v[8:9], off
	v_add_co_u32_e64 v50, s[0:1], s58, v2
	v_lshl_add_u64 v[48:49], v[0:1], 0, v[128:129]
	s_nop 0
	v_addc_co_u32_e64 v51, s[0:1], 0, v3, s[0:1]
	global_load_dwordx4 v[24:27], v[50:51], off
	global_load_dwordx4 v[28:31], v[48:49], off
	s_mov_b32 s0, 0x8000
	v_add_co_u32_e64 v52, s[0:1], s0, v48
	v_ashrrev_i32_e32 v0, 1, v104
	s_nop 0
	v_addc_co_u32_e64 v53, s[0:1], 0, v49, s[0:1]
	v_add_co_u32_e64 v54, s[0:1], s11, v48
	global_load_dwordx4 v[36:39], v[52:53], off
	s_nop 0
	v_addc_co_u32_e64 v55, s[0:1], 0, v49, s[0:1]
	global_load_dwordx4 v[40:43], v[54:55], off
	v_add_co_u32_e64 v56, s[0:1], s60, v48
	v_and_b32_e32 v134, 15, v104
	s_nop 0
	v_addc_co_u32_e64 v57, s[0:1], 0, v49, s[0:1]
	global_load_dwordx4 v[44:47], v[56:57], off
	v_and_b32_e32 v135, 0xffffffc0, v0
	v_lshlrev_b32_e32 v0, 7, v6
	v_xor_b32_e32 v1, v7, v104
	s_movk_i32 s0, 0x70
	v_bfe_u32 v128, v104, 6, 1
	v_lshlrev_b32_e32 v6, 7, v134
	v_and_or_b32 v0, v1, s0, v0
	v_lshl_or_b32 v59, v128, 13, v6
	v_add_u32_e32 v136, 0, v0
	global_load_dwordx4 v[0:3], v[2:3], off offset:128
	s_nop 0
	global_load_dwordx4 v[4:7], v[4:5], off offset:128
	s_nop 0
	global_load_dwordx4 v[8:11], v[8:9], off offset:128
	s_waitcnt vmcnt(10)
	ds_write_b128 v136, v[12:15]
	s_waitcnt vmcnt(9)
	ds_write_b128 v136, v[16:19] offset:4096
	s_waitcnt vmcnt(8)
	ds_write_b128 v136, v[20:23] offset:8192
	global_load_dwordx4 v[12:15], v[50:51], off offset:128
	global_load_dwordx4 v[16:19], v[48:49], off offset:128
	global_load_dwordx4 v[20:23], v[52:53], off offset:128
	v_lshrrev_b32_e32 v58, 4, v104
	v_bfe_u32 v105, v104, 1, 3
	v_add_u32_e32 v106, 0, v59
	s_waitcnt vmcnt(10)
	ds_write_b128 v136, v[24:27] offset:12288
	global_load_dwordx4 v[24:27], v[54:55], off offset:128
	s_waitcnt vmcnt(10)
	ds_write_b128 v136, v[28:31] offset:16384
	global_load_dwordx4 v[28:31], v[56:57], off offset:128
	v_bfe_u32 v137, v104, 4, 2
	v_bitop3_b32 v104, v137, v105, 4 bitop3:0x36
	v_lshlrev_b32_e32 v109, 4, v104
	v_add_u32_e32 v122, v106, v109
	s_mov_b64 s[0:1], 0x800000
	v_lshl_add_u64 v[34:35], v[34:35], 0, s[0:1]
	s_waitcnt vmcnt(10)
	ds_write_b128 v136, v[36:39] offset:20480
	v_bitop3_b32 v36, v58, v105, 3 bitop3:0x6c
	v_readlane_b32 s0, v251, 26
	s_waitcnt vmcnt(9)
	ds_write_b128 v136, v[40:43] offset:24576
	v_lshlrev_b32_e32 v40, 4, v36
	v_add_u32_e32 v120, v106, v40
	v_or_b32_e32 v41, v135, v134
	v_lshl_add_u32 v108, v41, 7, 0
	v_add_u32_e32 v121, v108, v40
	s_waitcnt vmcnt(8)
	ds_write_b128 v136, v[44:47] offset:28672
	s_waitcnt lgkmcnt(0)
	s_barrier
	ds_read_b128 v[36:39], v120 offset:16384
	ds_read_b128 v[48:51], v120 offset:18432
	ds_read_b128 v[56:59], v120 offset:20480
	ds_read_b128 v[64:67], v120 offset:22528
	ds_read_b128 v[40:43], v121
	ds_read_b128 v[68:71], v121 offset:2048
	ds_read_b128 v[84:87], v121 offset:4096
	ds_read_b128 v[100:103], v121 offset:6144
	ds_read_b128 v[104:107], v122 offset:16384
	v_add_u32_e32 v124, v108, v109
	ds_read_b128 v[108:111], v122 offset:18432
	ds_read_b128 v[112:115], v122 offset:20480
	ds_read_b128 v[116:119], v122 offset:22528
	s_waitcnt lgkmcnt(7)
	v_mfma_f32_16x16x32_bf16 v[44:47], v[36:39], v[40:43], 0
	v_cndmask_b32_e32 v33, v35, v33, vcc
	v_cndmask_b32_e32 v32, v34, v32, vcc
	v_readlane_b32 s1, v251, 27
	v_mfma_f32_16x16x32_bf16 v[52:55], v[48:51], v[40:43], 0
	s_nop 0
	v_lshl_add_u64 v[32:33], v[32:33], 1, s[0:1]
	s_movk_i32 s0, 0x4f
	v_mfma_f32_16x16x32_bf16 v[60:63], v[56:59], v[40:43], 0
	v_mfma_f32_16x16x32_bf16 v[40:43], v[64:67], v[40:43], 0
	s_waitcnt lgkmcnt(6)
	v_mfma_f32_16x16x32_bf16 v[72:75], v[36:39], v[68:71], 0
	v_mfma_f32_16x16x32_bf16 v[76:79], v[48:51], v[68:71], 0
	v_mfma_f32_16x16x32_bf16 v[80:83], v[56:59], v[68:71], 0
	v_mfma_f32_16x16x32_bf16 v[68:71], v[64:67], v[68:71], 0
	s_waitcnt lgkmcnt(5)
	v_mfma_f32_16x16x32_bf16 v[88:91], v[36:39], v[84:87], 0
	v_mfma_f32_16x16x32_bf16 v[92:95], v[48:51], v[84:87], 0
	v_mfma_f32_16x16x32_bf16 v[96:99], v[56:59], v[84:87], 0
	v_mfma_f32_16x16x32_bf16 v[84:87], v[64:67], v[84:87], 0
	s_waitcnt lgkmcnt(4)
	v_mfma_f32_16x16x32_bf16 v[36:39], v[36:39], v[100:103], 0
	v_mfma_f32_16x16x32_bf16 v[48:51], v[48:51], v[100:103], 0
	v_mfma_f32_16x16x32_bf16 v[56:59], v[56:59], v[100:103], 0
	v_mfma_f32_16x16x32_bf16 v[64:67], v[64:67], v[100:103], 0
	ds_read_b128 v[100:103], v124
	s_waitcnt lgkmcnt(0)
	v_mfma_f32_16x16x32_bf16 v[44:47], v[104:107], v[100:103], v[44:47]
	v_mfma_f32_16x16x32_bf16 v[52:55], v[108:111], v[100:103], v[52:55]
	v_mfma_f32_16x16x32_bf16 v[60:63], v[112:115], v[100:103], v[60:63]
	v_mfma_f32_16x16x32_bf16 v[40:43], v[116:119], v[100:103], v[40:43]
	ds_read_b128 v[100:103], v124 offset:2048
	s_waitcnt lgkmcnt(0)
	v_mfma_f32_16x16x32_bf16 v[72:75], v[104:107], v[100:103], v[72:75]
	v_mfma_f32_16x16x32_bf16 v[76:79], v[108:111], v[100:103], v[76:79]
	v_mfma_f32_16x16x32_bf16 v[80:83], v[112:115], v[100:103], v[80:83]
	v_mfma_f32_16x16x32_bf16 v[68:71], v[116:119], v[100:103], v[68:71]
	ds_read_b128 v[100:103], v124 offset:4096
	s_waitcnt lgkmcnt(0)
	v_mfma_f32_16x16x32_bf16 v[88:91], v[104:107], v[100:103], v[88:91]
	v_mfma_f32_16x16x32_bf16 v[92:95], v[108:111], v[100:103], v[92:95]
	v_mfma_f32_16x16x32_bf16 v[96:99], v[112:115], v[100:103], v[96:99]
	v_mfma_f32_16x16x32_bf16 v[84:87], v[116:119], v[100:103], v[84:87]
	ds_read_b128 v[100:103], v124 offset:6144
	s_waitcnt vmcnt(7)
	ds_write_b128 v136, v[0:3] offset:32768
	s_waitcnt vmcnt(6)
	ds_write_b128 v136, v[4:7] offset:36864
	s_waitcnt vmcnt(5)
	ds_write_b128 v136, v[8:11] offset:40960
	s_waitcnt vmcnt(4)
	ds_write_b128 v136, v[12:15] offset:45056
	s_waitcnt vmcnt(3)
	ds_write_b128 v136, v[16:19] offset:49152
	s_waitcnt vmcnt(2)
	ds_write_b128 v136, v[20:23] offset:53248
	s_waitcnt vmcnt(1)
	ds_write_b128 v136, v[24:27] offset:57344
	s_waitcnt vmcnt(0)
	ds_write_b128 v136, v[28:31] offset:61440
	s_waitcnt lgkmcnt(0)
	v_mfma_f32_16x16x32_bf16 v[36:39], v[104:107], v[100:103], v[36:39]
	s_barrier
	ds_read_b128 v[104:107], v120 offset:49152
	v_mfma_f32_16x16x32_bf16 v[48:51], v[108:111], v[100:103], v[48:51]
	ds_read_b128 v[108:111], v120 offset:51200
	v_mfma_f32_16x16x32_bf16 v[56:59], v[112:115], v[100:103], v[56:59]
	ds_read_b128 v[112:115], v120 offset:53248
	v_mfma_f32_16x16x32_bf16 v[64:67], v[116:119], v[100:103], v[64:67]
	ds_read_b128 v[116:119], v120 offset:55296
	ds_read_b128 v[100:103], v121 offset:32768
	s_waitcnt lgkmcnt(0)
	v_mfma_f32_16x16x32_bf16 v[44:47], v[104:107], v[100:103], v[44:47]
	v_mfma_f32_16x16x32_bf16 v[52:55], v[108:111], v[100:103], v[52:55]
	v_mfma_f32_16x16x32_bf16 v[60:63], v[112:115], v[100:103], v[60:63]
	v_mfma_f32_16x16x32_bf16 v[40:43], v[116:119], v[100:103], v[40:43]
	ds_read_b128 v[100:103], v121 offset:34816
	s_waitcnt lgkmcnt(0)
	v_mfma_f32_16x16x32_bf16 v[72:75], v[104:107], v[100:103], v[72:75]
	v_mfma_f32_16x16x32_bf16 v[76:79], v[108:111], v[100:103], v[76:79]
	v_mfma_f32_16x16x32_bf16 v[80:83], v[112:115], v[100:103], v[80:83]
	v_mfma_f32_16x16x32_bf16 v[68:71], v[116:119], v[100:103], v[68:71]
	ds_read_b128 v[100:103], v121 offset:36864
	s_waitcnt lgkmcnt(0)
	v_mfma_f32_16x16x32_bf16 v[88:91], v[104:107], v[100:103], v[88:91]
	v_mfma_f32_16x16x32_bf16 v[92:95], v[108:111], v[100:103], v[92:95]
	v_mfma_f32_16x16x32_bf16 v[96:99], v[112:115], v[100:103], v[96:99]
	v_mfma_f32_16x16x32_bf16 v[84:87], v[116:119], v[100:103], v[84:87]
	ds_read_b128 v[100:103], v121 offset:38912
	s_waitcnt lgkmcnt(0)
	v_mfma_f32_16x16x32_bf16 v[36:39], v[104:107], v[100:103], v[36:39]
	ds_read_b128 v[104:107], v122 offset:49152
	v_mfma_f32_16x16x32_bf16 v[48:51], v[108:111], v[100:103], v[48:51]
	ds_read_b128 v[108:111], v122 offset:51200
	v_mfma_f32_16x16x32_bf16 v[56:59], v[112:115], v[100:103], v[56:59]
	ds_read_b128 v[112:115], v122 offset:53248
	v_mfma_f32_16x16x32_bf16 v[64:67], v[116:119], v[100:103], v[64:67]
	ds_read_b128 v[116:119], v122 offset:55296
	ds_read_b128 v[100:103], v124 offset:32768
	s_waitcnt lgkmcnt(0)
	v_mfma_f32_16x16x32_bf16 v[44:47], v[104:107], v[100:103], v[44:47]
	v_mfma_f32_16x16x32_bf16 v[52:55], v[108:111], v[100:103], v[52:55]
	v_mfma_f32_16x16x32_bf16 v[60:63], v[112:115], v[100:103], v[60:63]
	v_mfma_f32_16x16x32_bf16 v[40:43], v[116:119], v[100:103], v[40:43]
	ds_read_b128 v[100:103], v124 offset:34816
	ds_read_b128 v[120:123], v124 offset:36864
	ds_read_b128 v[124:127], v124 offset:38912
	ds_write_b128 v136, v[0:3]
	v_or_b32_e32 v0, v134, v132
	v_add_u32_e32 v0, v0, v135
	ds_write_b128 v136, v[4:7] offset:4096
	ds_write_b128 v136, v[8:11] offset:8192
	ds_write_b128 v136, v[12:15] offset:12288
	ds_write_b128 v136, v[16:19] offset:16384
	ds_write_b128 v136, v[20:23] offset:20480
	ds_write_b128 v136, v[24:27] offset:24576
	s_waitcnt lgkmcnt(8)
	v_mfma_f32_16x16x32_bf16 v[20:23], v[116:119], v[120:123], v[84:87]
	v_lshlrev_b32_e32 v1, 6, v128
	v_lshlrev_b32_e32 v2, 2, v137
	ds_write_b128 v136, v[28:31] offset:28672
	v_and_or_b32 v85, v0, s0, v130
	v_cndmask_b32_e64 v86, 11, 9, vcc
	v_or3_b32 v84, v1, v2, v133
	v_lshlrev_b32_e32 v1, v86, v85
	v_lshlrev_b32_e32 v128, 1, v1
	v_ashrrev_i32_e32 v0, 7, v0
	v_cndmask_b32_e64 v1, 10, 8, vcc
	s_waitcnt lgkmcnt(8)
	v_mfma_f32_16x16x32_bf16 v[24:27], v[104:107], v[124:127], v[36:39]
	v_lshl_add_u64 v[34:35], v[32:33], 0, v[128:129]
	v_lshlrev_b32_e32 v128, 1, v84
	s_waitcnt lgkmcnt(0)
	v_lshlrev_b32_e32 v36, v1, v0
	v_and_b32_sdwa v38, v46, v170 dst_sel:DWORD dst_unused:UNUSED_PAD src0_sel:WORD_1 src1_sel:DWORD
	v_and_b32_sdwa v39, v44, v170 dst_sel:DWORD dst_unused:UNUSED_PAD src0_sel:WORD_1 src1_sel:DWORD
	v_ashrrev_i32_e32 v37, 31, v36
	v_add3_u32 v44, v44, v39, s56
	v_add3_u32 v38, v46, v38, s56
	v_and_b32_sdwa v39, v47, v170 dst_sel:DWORD dst_unused:UNUSED_PAD src0_sel:WORD_1 src1_sel:DWORD
	v_and_b32_sdwa v46, v45, v170 dst_sel:DWORD dst_unused:UNUSED_PAD src0_sel:WORD_1 src1_sel:DWORD
	v_lshlrev_b64 v[36:37], 1, v[36:37]
	v_add3_u32 v39, v47, v39, s56
	v_add3_u32 v45, v45, v46, s56
	v_lshl_add_u64 v[34:35], v[34:35], 0, v[36:37]
	v_and_b32_e32 v39, 0xffff0000, v39
	v_and_b32_e32 v45, 0xffff0000, v45
	v_lshl_add_u64 v[34:35], v[34:35], 0, v[128:129]
	v_or_b32_sdwa v39, v39, v38 dst_sel:DWORD dst_unused:UNUSED_PAD src0_sel:DWORD src1_sel:WORD_1
	v_or_b32_sdwa v38, v45, v44 dst_sel:DWORD dst_unused:UNUSED_PAD src0_sel:DWORD src1_sel:WORD_1
	s_barrier
	global_store_dwordx2 v[34:35], v[38:39], off
	v_cvt_pk_bf16_f32 v39, v54, v55
	v_cvt_pk_bf16_f32 v38, v52, v53
	global_store_dwordx2 v[34:35], v[38:39], off offset:32
	v_cvt_pk_bf16_f32 v39, v62, v63
	v_cvt_pk_bf16_f32 v38, v60, v61
	global_store_dwordx2 v[34:35], v[38:39], off offset:64
	v_and_b32_sdwa v38, v42, v170 dst_sel:DWORD dst_unused:UNUSED_PAD src0_sel:WORD_1 src1_sel:DWORD
	v_and_b32_sdwa v39, v40, v170 dst_sel:DWORD dst_unused:UNUSED_PAD src0_sel:WORD_1 src1_sel:DWORD
	v_add3_u32 v40, v40, v39, s56
	v_add3_u32 v38, v42, v38, s56
	v_and_b32_sdwa v39, v43, v170 dst_sel:DWORD dst_unused:UNUSED_PAD src0_sel:WORD_1 src1_sel:DWORD
	v_and_b32_sdwa v42, v41, v170 dst_sel:DWORD dst_unused:UNUSED_PAD src0_sel:WORD_1 src1_sel:DWORD
	v_mfma_f32_16x16x32_bf16 v[72:75], v[104:107], v[100:103], v[72:75]
	v_add3_u32 v39, v43, v39, s56
	v_add3_u32 v41, v41, v42, s56
	v_and_b32_e32 v39, 0xffff0000, v39
	v_and_b32_e32 v41, 0xffff0000, v41
	v_or_b32_sdwa v39, v39, v38 dst_sel:DWORD dst_unused:UNUSED_PAD src0_sel:DWORD src1_sel:WORD_1
	v_or_b32_sdwa v38, v41, v40 dst_sel:DWORD dst_unused:UNUSED_PAD src0_sel:DWORD src1_sel:WORD_1
	global_store_dwordx2 v[34:35], v[38:39], off offset:96
	v_or_b32_e32 v34, 16, v85
	v_lshlrev_b32_e32 v34, v86, v34
	v_mfma_f32_16x16x32_bf16 v[76:79], v[108:111], v[100:103], v[76:79]
	v_lshlrev_b32_e32 v34, 1, v34
	v_mov_b32_e32 v35, v129
	v_lshl_add_u64 v[34:35], v[32:33], 0, v[34:35]
	v_lshl_add_u64 v[34:35], v[34:35], 0, v[36:37]
	v_lshl_add_u64 v[34:35], v[34:35], 0, v[128:129]
	v_cvt_pk_bf16_f32 v39, v74, v75
	v_cvt_pk_bf16_f32 v38, v72, v73
	global_store_dwordx2 v[34:35], v[38:39], off
	v_mfma_f32_16x16x32_bf16 v[80:83], v[112:115], v[100:103], v[80:83]
	v_cvt_pk_bf16_f32 v39, v78, v79
	v_cvt_pk_bf16_f32 v38, v76, v77
	global_store_dwordx2 v[34:35], v[38:39], off offset:32
	v_mfma_f32_16x16x32_bf16 v[68:71], v[116:119], v[100:103], v[68:71]
	s_nop 3
	v_cvt_pk_bf16_f32 v39, v82, v83
	s_nop 2
	v_cvt_pk_bf16_f32 v38, v80, v81
	global_store_dwordx2 v[34:35], v[38:39], off offset:64
	v_mfma_f32_16x16x32_bf16 v[8:11], v[104:107], v[120:123], v[88:91]
	s_nop 3
	v_cvt_pk_bf16_f32 v39, v70, v71
	s_nop 2
	v_cvt_pk_bf16_f32 v38, v68, v69
	global_store_dwordx2 v[34:35], v[38:39], off offset:96
	v_or_b32_e32 v34, 32, v85
	v_lshlrev_b32_e32 v34, v86, v34
	s_nop 2
	v_and_b32_sdwa v39, v8, v170 dst_sel:DWORD dst_unused:UNUSED_PAD src0_sel:WORD_1 src1_sel:DWORD
	v_mfma_f32_16x16x32_bf16 v[12:15], v[108:111], v[120:123], v[92:95]
	v_lshlrev_b32_e32 v34, 1, v34
	v_mov_b32_e32 v35, v129
	v_add3_u32 v8, v8, v39, s56
	v_and_b32_sdwa v39, v9, v170 dst_sel:DWORD dst_unused:UNUSED_PAD src0_sel:WORD_1 src1_sel:DWORD
	v_lshl_add_u64 v[34:35], v[32:33], 0, v[34:35]
	v_add3_u32 v9, v9, v39, s56
	v_lshl_add_u64 v[34:35], v[34:35], 0, v[36:37]
	v_and_b32_e32 v38, 0xffff0000, v9
	v_lshl_add_u64 v[34:35], v[34:35], 0, v[128:129]
	v_cvt_pk_bf16_f32 v9, v10, v11
	v_or_b32_sdwa v8, v38, v8 dst_sel:DWORD dst_unused:UNUSED_PAD src0_sel:DWORD src1_sel:WORD_1
	global_store_dwordx2 v[34:35], v[8:9], off
	v_mfma_f32_16x16x32_bf16 v[16:19], v[112:115], v[120:123], v[96:99]
	v_cvt_pk_bf16_f32 v9, v14, v15
	v_cvt_pk_bf16_f32 v8, v12, v13
	global_store_dwordx2 v[34:35], v[8:9], off offset:32
	s_nop 4
	v_cvt_pk_bf16_f32 v9, v18, v19
	s_nop 3
	v_cvt_pk_bf16_f32 v8, v16, v17
	global_store_dwordx2 v[34:35], v[8:9], off offset:64
	v_cvt_pk_bf16_f32 v9, v22, v23
	v_cvt_pk_bf16_f32 v8, v20, v21
	global_store_dwordx2 v[34:35], v[8:9], off offset:96
	v_or_b32_e32 v8, 48, v85
	v_lshlrev_b32_e32 v8, v86, v8
	v_mfma_f32_16x16x32_bf16 v[28:31], v[108:111], v[124:127], v[48:51]
	v_lshlrev_b32_e32 v8, 1, v8
	v_mov_b32_e32 v9, v129
	v_lshl_add_u64 v[8:9], v[32:33], 0, v[8:9]
	v_lshl_add_u64 v[8:9], v[8:9], 0, v[36:37]
	v_lshl_add_u64 v[8:9], v[8:9], 0, v[128:129]
	v_cvt_pk_bf16_f32 v11, v26, v27
	v_cvt_pk_bf16_f32 v10, v24, v25
	global_store_dwordx2 v[8:9], v[10:11], off
	v_mfma_f32_16x16x32_bf16 v[4:7], v[112:115], v[124:127], v[56:59]
	v_cvt_pk_bf16_f32 v11, v30, v31
	v_cvt_pk_bf16_f32 v10, v28, v29
	global_store_dwordx2 v[8:9], v[10:11], off offset:32
	s_nop 4
	v_and_b32_sdwa v11, v4, v170 dst_sel:DWORD dst_unused:UNUSED_PAD src0_sel:WORD_1 src1_sel:DWORD
	v_mfma_f32_16x16x32_bf16 v[0:3], v[116:119], v[124:127], v[64:67]
	s_nop 2
	v_add3_u32 v4, v4, v11, s56
	s_nop 1
	v_and_b32_sdwa v11, v5, v170 dst_sel:DWORD dst_unused:UNUSED_PAD src0_sel:WORD_1 src1_sel:DWORD
	s_nop 0
	v_add3_u32 v5, v5, v11, s56
	v_and_b32_e32 v10, 0xffff0000, v5
	v_cvt_pk_bf16_f32 v5, v6, v7
	v_or_b32_sdwa v4, v10, v4 dst_sel:DWORD dst_unused:UNUSED_PAD src0_sel:DWORD src1_sel:WORD_1
	global_store_dwordx2 v[8:9], v[4:5], off offset:64
	s_nop 0
	v_bfe_u32 v4, v0, 16, 1
	v_add3_u32 v0, v0, v4, s56
	v_bfe_u32 v4, v1, 16, 1
	v_lshrrev_b32_e32 v0, 16, v0
	v_add3_u32 v1, v1, v4, s56
	v_and_or_b32 v4, v1, s5, v0
	v_bfe_u32 v0, v2, 16, 1
	v_add3_u32 v0, v2, v0, s56
	v_bfe_u32 v1, v3, 16, 1
	v_lshrrev_b32_e32 v0, 16, v0
	v_add3_u32 v1, v3, v1, s56
	s_mov_b64 s[0:1], 0x60
	v_and_or_b32 v2, v1, s5, v0
	v_lshl_add_u64 v[0:1], v[8:9], 0, s[0:1]
	global_store_dword v[8:9], v4, off offset:96

.LBB0_435:
	s_or_b64 exec, exec, s[0:1]
	s_mov_b64 s[0:1], src_shared_base
	s_add_i32 s0, 0, 0x11fe0
	s_cmp_lg_u32 s0, -1
	s_cselect_b32 s0, s0, 0
	s_cselect_b32 s1, s1, 0
	v_mov_b32_e32 v0, s0
	v_mov_b32_e32 v1, s1
	s_waitcnt lgkmcnt(0)
	s_barrier
	s_waitcnt vmcnt(11)
	ds_read_b32 v32, v0
	s_waitcnt lgkmcnt(0)
	v_readlane_b32 s0, v254, 54
	s_waitcnt lgkmcnt(0)
	s_nop 0
	v_cmp_gt_i32_e32 vcc, s0, v32
	s_mov_b64 s[0:1], -1
	s_and_saveexec_b64 s[96:97], vcc
	s_cbranch_execz .LBB0_430
	s_movk_i32 s0, 0x600
	v_cmp_gt_i32_e32 vcc, s0, v32
	s_and_saveexec_b64 s[0:1], vcc
	s_xor_b64 s[0:1], exec, s[0:1]
	v_writelane_b32 v255, s0, 2
	s_nop 1
	v_writelane_b32 v255, s1, 3
	s_cbranch_execz .LBB0_560
	s_movk_i32 s0, 0x500
	v_cmp_gt_i32_e32 vcc, s0, v32
	s_and_saveexec_b64 s[0:1], vcc
	s_xor_b64 s[0:1], exec, s[0:1]
	v_writelane_b32 v255, s0, 4
	s_nop 1
	v_writelane_b32 v255, s1, 5
	s_cbranch_execz .LBB0_551
	s_movk_i32 s0, 0x7f
	v_cmp_lt_i32_e32 vcc, s0, v32
	s_and_saveexec_b64 s[0:1], vcc
	s_xor_b64 s[0:1], exec, s[0:1]
	s_cbranch_execz .LBB0_526
	v_writelane_b32 v255, s0, 6
	v_cmp_lt_u32_e32 vcc, s89, v32
	s_nop 0
	v_writelane_b32 v255, s1, 7
	s_and_saveexec_b64 s[0:1], vcc
	s_xor_b64 s[16:17], exec, s[0:1]
	s_cbranch_execz .LBB0_507
	s_movk_i32 s0, 0x2ff
	v_cmp_lt_u32_e32 vcc, s0, v32
	s_and_saveexec_b64 s[0:1], vcc
	s_xor_b64 s[0:1], exec, s[0:1]
	s_cbranch_execz .LBB0_448
	v_add_u32_e32 v0, 0xfffffd00, v32
	v_mov_b32_e32 v35, v166
	v_lshrrev_b32_e32 v33, 4, v0
	v_bfe_u32 v34, v32, 3, 1
	v_lshlrev_b32_e32 v69, 8, v33
	v_ashrrev_i32_e32 v0, 6, v35
	v_lshl_add_u32 v36, v34, 2, v0
	v_lshlrev_b32_e32 v0, 5, v32
	v_and_b32_e32 v68, 15, v35
	v_and_b32_e32 v70, 0xe0, v0
	v_lshlrev_b32_e32 v48, 6, v36
	v_ashrrev_i32_e32 v49, 31, v48
	v_or3_b32 v2, v70, v68, v69
	v_bfe_u32 v53, v35, 4, 2
	v_lshl_add_u64 v[0:1], v[48:49], 2, s[30:31]
	v_lshlrev_b32_e32 v128, 13, v2
	v_lshl_add_u64 v[16:17], v[0:1], 0, v[128:129]
	v_lshlrev_b32_e32 v128, 5, v53
	s_mov_b64 s[2:3], 0x20000
	v_lshl_add_u64 v[12:13], v[16:17], 0, v[128:129]
	v_lshl_add_u64 v[24:25], v[16:17], 0, s[2:3]
	global_load_dwordx4 v[0:3], v[12:13], off
	global_load_dwordx4 v[4:7], v[12:13], off offset:16
	global_load_dwordx4 v[8:11], v[12:13], off offset:128
	s_nop 0
	global_load_dwordx4 v[12:15], v[12:13], off offset:144
	v_lshl_add_u64 v[20:21], v[24:25], 0, v[128:129]
	global_load_dwordx4 v[16:19], v[20:21], off
	s_nop 0
	global_load_dwordx4 v[20:23], v[20:21], off offset:16
	v_or_b32_e32 v128, 0x80, v128
	v_lshl_add_u64 v[28:29], v[24:25], 0, v[128:129]
	global_load_dwordx4 v[24:27], v[28:29], off
	s_nop 0
	global_load_dwordx4 v[28:31], v[28:29], off offset:16
	s_mov_b32 s2, 0x3e000000
	v_readlane_b32 s68, v254, 8
	v_readlane_b32 s69, v254, 9
	v_ashrrev_i32_e32 v73, 3, v35
	v_and_b32_e32 v58, 7, v35
	v_lshlrev_b32_e32 v128, 8, v34
	v_cmp_eq_u32_e32 vcc, 0, v53
	v_lshrrev_b32_e32 v32, 4, v35
	v_lshl_add_u32 v59, v53, 3, 0
	v_mul_u32_u24_e32 v67, 0x50, v68
	s_mov_b32 s24, 0
	v_add_u32_e32 v79, v59, v67
	v_bfe_u32 v79, v166, 4, 2
	v_bfe_u32 v67, v166, 3, 1
	v_xor_b32_e32 v79, v79, v67
	v_lshlrev_b32_e32 v79, 3, v79
	v_and_b32_e32 v67, 15, v166
	v_lshl_or_b32 v79, v67, 6, v79
	v_readlane_b32 s70, v254, 10
	v_readlane_b32 s71, v254, 11
	v_readlane_b32 s72, v254, 12
	v_readlane_b32 s73, v254, 13
	v_readlane_b32 s74, v254, 14
	v_readlane_b32 s75, v254, 15
	v_readlane_b32 s76, v254, 16
	v_readlane_b32 s77, v254, 17
	v_readlane_b32 s78, v254, 18
	v_readlane_b32 s79, v254, 19
	v_readlane_b32 s80, v254, 20
	v_readlane_b32 s81, v254, 21
	v_readlane_b32 s82, v254, 22
	v_readlane_b32 s83, v254, 23
	s_waitcnt vmcnt(7)
	v_pk_mul_f32 v[0:1], v[0:1], s[2:3] op_sel_hi:[1,0]
	v_pk_mul_f32 v[2:3], v[2:3], s[2:3] op_sel_hi:[1,0]
	s_waitcnt vmcnt(6)
	v_pk_mul_f32 v[4:5], v[4:5], s[2:3] op_sel_hi:[1,0]
	v_pk_mul_f32 v[6:7], v[6:7], s[2:3] op_sel_hi:[1,0]
	s_waitcnt vmcnt(5)
	v_pk_mul_f32 v[8:9], v[8:9], s[2:3] op_sel_hi:[1,0]
	v_pk_mul_f32 v[10:11], v[10:11], s[2:3] op_sel_hi:[1,0]
	s_waitcnt vmcnt(4)
	v_pk_mul_f32 v[14:15], v[14:15], s[2:3] op_sel_hi:[1,0]
	v_pk_mul_f32 v[12:13], v[12:13], s[2:3] op_sel_hi:[1,0]
	v_bfe_u32 v37, v7, 16, 1
	v_bfe_u32 v39, v3, 16, 1
	v_bfe_u32 v41, v5, 16, 1
	v_bfe_u32 v42, v4, 16, 1
	v_bfe_u32 v43, v1, 16, 1
	v_bfe_u32 v44, v0, 16, 1
	v_bfe_u32 v45, v15, 16, 1
	v_bfe_u32 v46, v14, 16, 1
	v_bfe_u32 v47, v11, 16, 1
	v_bfe_u32 v50, v10, 16, 1
	v_bfe_u32 v54, v9, 16, 1
	v_bfe_u32 v55, v8, 16, 1
	s_waitcnt vmcnt(3)
	v_pk_mul_f32 v[16:17], v[16:17], s[2:3] op_sel_hi:[1,0]
	s_waitcnt vmcnt(2)
	v_pk_mul_f32 v[20:21], v[20:21], s[2:3] op_sel_hi:[1,0]
	v_bfe_u32 v51, v13, 16, 1
	v_bfe_u32 v52, v12, 16, 1
	v_add3_u32 v3, v3, v39, s56
	v_add3_u32 v7, v7, v37, s56
	v_add3_u32 v37, v0, v44, s56
	v_add3_u32 v1, v1, v43, s56
	v_add3_u32 v39, v4, v42, s56
	v_add3_u32 v5, v5, v41, s56
	v_add3_u32 v41, v10, v50, s56
	v_add3_u32 v42, v11, v47, s56
	v_add3_u32 v43, v14, v46, s56
	v_add3_u32 v44, v15, v45, s56
	v_add3_u32 v45, v8, v55, s56
	v_add3_u32 v46, v9, v54, s56
	v_bfe_u32 v8, v21, 16, 1
	v_bfe_u32 v9, v20, 16, 1
	v_bfe_u32 v10, v17, 16, 1
	v_bfe_u32 v11, v16, 16, 1
	v_pk_mul_f32 v[18:19], v[18:19], s[2:3] op_sel_hi:[1,0]
	v_pk_mul_f32 v[22:23], v[22:23], s[2:3] op_sel_hi:[1,0]
	v_add3_u32 v47, v12, v52, s56
	v_add3_u32 v51, v13, v51, s56
	v_add3_u32 v56, v16, v11, s56
	v_add3_u32 v57, v17, v10, s56
	v_add3_u32 v20, v20, v9, s56
	v_add3_u32 v21, v21, v8, s56
	s_waitcnt vmcnt(1)
	v_pk_mul_f32 v[8:9], v[24:25], s[2:3] op_sel_hi:[1,0]
	v_pk_mul_f32 v[10:11], v[26:27], s[2:3] op_sel_hi:[1,0]
	s_waitcnt vmcnt(0)
	v_pk_mul_f32 v[12:13], v[28:29], s[2:3] op_sel_hi:[1,0]
	v_pk_mul_f32 v[14:15], v[30:31], s[2:3] op_sel_hi:[1,0]
	v_readlane_b32 s2, v254, 56
	v_bfe_u32 v24, v15, 16, 1
	v_bfe_u32 v29, v8, 16, 1
	v_add_u32_e32 v16, s2, v36
	v_ashrrev_i32_e32 v17, 31, v16
	v_lshl_add_u64 v[16:17], v[16:17], 2, s[68:69]
	global_load_dword v81, v[16:17], off
	v_bfe_u32 v25, v14, 16, 1
	v_bfe_u32 v28, v9, 16, 1
	v_add3_u32 v15, v15, v24, s56
	v_add3_u32 v24, v8, v29, s56
	v_add_u32_e32 v8, v73, v69
	v_add3_u32 v14, v14, v25, s56
	v_add3_u32 v25, v9, v28, s56
	v_ashrrev_i32_e32 v9, 31, v8
	v_mbcnt_lo_u32_b32 v28, -1, 0
	v_bfe_u32 v40, v2, 16, 1
	v_lshlrev_b64 v[8:9], 13, v[8:9]
	v_mbcnt_hi_u32_b32 v28, -1, v28
	v_bfe_u32 v38, v6, 16, 1
	v_add3_u32 v40, v2, v40, s56
	v_bfe_u32 v2, v22, 16, 1
	v_bfe_u32 v4, v19, 16, 1
	v_lshl_add_u64 v[8:9], s[30:31], 0, v[8:9]
	v_and_b32_e32 v30, 64, v28
	v_add3_u32 v38, v6, v38, s56
	v_bfe_u32 v6, v18, 16, 1
	v_add3_u32 v19, v19, v4, s56
	v_add3_u32 v22, v22, v2, s56
	v_lshlrev_b32_e32 v2, 2, v35
	v_lshlrev_b32_e32 v4, 3, v58
	v_lshl_add_u64 v[8:9], v[8:9], 0, v[128:129]
	s_mov_b64 s[2:3], 0xa00
	v_xor_b32_e32 v29, 16, v28
	v_add_u32_e32 v30, 64, v30
	v_add3_u32 v18, v18, v6, s56
	v_cndmask_b32_e64 v50, 0, 1.0, vcc
	v_and_b32_e32 v2, 12, v2
	v_and_b32_e32 v6, 32, v4
	v_lshl_add_u64 v[64:65], v[8:9], 0, s[2:3]
	s_mov_b64 s[2:3], 0x800
	v_cmp_lt_i32_e32 vcc, v29, v30
	v_lshl_add_u64 v[62:63], v[8:9], 0, s[2:3]
	v_or_b32_e32 v9, v6, v2
	v_cndmask_b32_e32 v29, v28, v29, vcc
	v_bfe_u32 v16, v13, 16, 1
	v_bfe_u32 v17, v12, 16, 1
	v_bfe_u32 v8, v35, 4, 3
	v_lshrrev_b32_e32 v9, 3, v9
	v_lshlrev_b32_e32 v72, 2, v29
	v_xor_b32_e32 v29, 32, v28
	v_add3_u32 v12, v12, v17, s56
	v_add3_u32 v13, v13, v16, s56
	v_lshl_add_u32 v16, v73, 7, 0
	v_bitop3_b32 v17, v9, v32, 7 bitop3:0x78
	v_bitop3_b32 v8, v9, v8, 2 bitop3:0x36
	v_cmp_lt_i32_e32 vcc, v29, v30
	v_bfe_u32 v26, v11, 16, 1
	v_lshl_add_u32 v17, v17, 4, v16
	v_lshl_add_u32 v8, v8, 4, v16
	v_readlane_b32 s2, v254, 63
	v_bfe_u32 v16, v35, 1, 3
	v_cndmask_b32_e32 v28, v28, v29, vcc
	v_bfe_u32 v0, v23, 16, 1
	v_bfe_u32 v27, v10, 16, 1
	v_add3_u32 v11, v11, v26, s56
	v_lshlrev_b32_e32 v26, 3, v35
	v_lshl_or_b32 v54, v33, 9, s2
	v_lshlrev_b32_e32 v71, 2, v28
	s_movk_i32 s2, 0x280
	v_bitop3_b32 v28, v32, v16, 3 bitop3:0x6c
	v_bitop3_b32 v16, v53, v16, 4 bitop3:0x36
	v_add3_u32 v23, v23, v0, s56
	v_mov_b32_e32 v0, 0
	v_add3_u32 v10, v10, v27, s56
	v_and_b32_e32 v26, 8, v26
	v_lshlrev_b32_e32 v9, 1, v73
	v_lshl_add_u32 v27, v68, 7, 0
	v_mad_u32_u24 v61, v58, s2, 0
	v_lshlrev_b32_e32 v66, 4, v28
	v_lshlrev_b32_e32 v16, 4, v16
	s_mov_b32 s2, 0x7060302
	v_lshlrev_b32_e32 v52, 6, v34
	v_mov_b32_e32 v55, v129
	v_perm_b32 v31, v7, v38, s2
	v_perm_b32 v29, v3, v40, s2
	v_perm_b32 v30, v5, v39, s2
	v_perm_b32 v28, v1, v37, s2
	v_perm_b32 v35, v44, v43, s2
	v_perm_b32 v33, v42, v41, s2
	v_perm_b32 v34, v51, v47, s2
	v_perm_b32 v32, v46, v45, s2
	v_perm_b32 v39, v23, v22, s2
	v_perm_b32 v37, v19, v18, s2
	v_perm_b32 v38, v21, v20, s2
	v_perm_b32 v36, v57, v56, s2
	v_perm_b32 v47, v15, v14, s2
	v_perm_b32 v45, v11, v10, s2
	v_perm_b32 v46, v13, v12, s2
	v_perm_b32 v44, v25, v24, s2
	v_lshl_add_u64 v[56:57], s[30:31], 0, v[128:129]
	v_lshlrev_b32_e32 v128, 2, v4
	v_lshlrev_b32_e32 v58, 2, v6
	v_lshlrev_b32_e32 v60, 2, v2
	v_add_u32_e32 v74, v17, v26
	v_add_u32_e32 v75, v8, v26
	v_add_u32_e32 v76, v61, v9
	v_and_b32_e32 v76, 7, v166
	v_lshlrev_b32_e32 v76, 9, v76
	v_lshrrev_b32_e32 v77, 5, v166
	v_xor_b32_e32 v77, v77, v166
	v_and_b32_e32 v77, 7, v77
	v_lshl_or_b32 v76, v77, 3, v76
	v_bfe_u32 v77, v166, 3, 2
	v_lshl_or_b32 v76, v77, 1, v76
	v_add_u32_e32 v77, v27, v66
	v_add_u32_e32 v78, v27, v16
	s_waitcnt vmcnt(0)
	v_mov_b32_e32 v80, v81
	v_mov_b32_e32 v1, v0
	v_mov_b32_e32 v2, v0
	v_mov_b32_e32 v3, v0
	v_mov_b32_e32 v4, v0
	v_mov_b32_e32 v5, v0
	v_mov_b32_e32 v6, v0
	v_mov_b32_e32 v7, v0
	v_mov_b32_e32 v8, v0
	v_mov_b32_e32 v9, v0
	v_mov_b32_e32 v10, v0
	v_mov_b32_e32 v11, v0
	v_mov_b32_e32 v12, v0
	v_mov_b32_e32 v13, v0
	v_mov_b32_e32 v14, v0
	v_mov_b32_e32 v15, v0
	v_mov_b32_e32 v16, v0
	v_mov_b32_e32 v17, v0
	v_mov_b32_e32 v18, v0
	v_mov_b32_e32 v19, v0
	v_mov_b32_e32 v20, v0
	v_mov_b32_e32 v21, v0
	v_mov_b32_e32 v22, v0
	v_mov_b32_e32 v23, v0
	v_mov_b32_e32 v24, v0
	v_mov_b32_e32 v25, v0
	v_mov_b32_e32 v26, v0
	v_mov_b32_e32 v27, v0
	v_mov_b32_e32 v40, v0
	v_mov_b32_e32 v41, v0
	v_mov_b32_e32 v42, v0
	v_mov_b32_e32 v43, v0
	v_mov_b32_e32 v51, v50
	s_branch .LBB0_443
